# v1 + compact LDS-DMA blocks in diff-attn main loop: m0 written directly, no m0 save/restore, no s_nop (24 fewer instr per 2 tiles per wave)
# baseline (speedup 1.0000x reference)
.LBB0_495:
	s_waitcnt lgkmcnt(14)
	v_mfma_f32_32x32x16_bf16 v[52:67], v[144:147], v[196:199], v[52:67]
	v_exp_f32_e32 v116, v116
	v_exp_f32_e32 v117, v117
	ds_read_b64_tr_b16 v[80:81], v231 offset:26624
	ds_read_b64_tr_b16 v[82:83], v231 offset:27136
	s_waitcnt lgkmcnt(14)
	v_mfma_f32_32x32x16_bf16 v[36:51], v[144:147], v[84:87], v[36:51]
	v_exp_f32_e32 v118, v118
	v_exp_f32_e32 v119, v119
	ds_read_b64_tr_b16 v[84:85], v231 offset:30720
	ds_read_b64_tr_b16 v[86:87], v231 offset:31232
	s_waitcnt lgkmcnt(14)
	v_mfma_f32_32x32x16_bf16 v[20:35], v[144:147], v[88:91], v[20:35]
	v_exp_f32_e32 v120, v120
	v_exp_f32_e32 v121, v121
	ds_read_b64_tr_b16 v[88:89], v231 offset:34816
	ds_read_b64_tr_b16 v[90:91], v231 offset:35328
	s_waitcnt lgkmcnt(14)
	v_mfma_f32_32x32x16_bf16 v[4:19], v[144:147], v[92:95], v[4:19]
	v_exp_f32_e32 v122, v122
	v_exp_f32_e32 v123, v123
	ds_read_b64_tr_b16 v[92:93], v231 offset:38912
	ds_read_b64_tr_b16 v[94:95], v231 offset:39424
	s_waitcnt lgkmcnt(14)
	v_mfma_f32_32x32x16_bf16 v[52:67], v[140:143], v[96:99], v[52:67]
	v_exp_f32_e32 v124, v124
	v_exp_f32_e32 v125, v125
	ds_read_b64_tr_b16 v[96:97], v231 offset:27648
	ds_read_b64_tr_b16 v[98:99], v231 offset:28160
	s_waitcnt lgkmcnt(14)
	v_mfma_f32_32x32x16_bf16 v[36:51], v[140:143], v[68:71], v[36:51]
	v_exp_f32_e32 v126, v126
	v_exp_f32_e32 v127, v127
	ds_read_b64_tr_b16 v[188:189], v231 offset:31744
	ds_read_b64_tr_b16 v[190:191], v231 offset:32256
	s_waitcnt lgkmcnt(14)
	v_mfma_f32_32x32x16_bf16 v[20:35], v[140:143], v[72:75], v[20:35]
	v_exp_f32_e32 v128, v128
	v_exp_f32_e32 v129, v129
	ds_read_b64_tr_b16 v[206:207], v231 offset:35840
	ds_read_b64_tr_b16 v[208:209], v231 offset:36352
	s_waitcnt lgkmcnt(14)
	v_mfma_f32_32x32x16_bf16 v[4:19], v[140:143], v[76:79], v[4:19]
	v_exp_f32_e32 v130, v130
	v_exp_f32_e32 v131, v131
	ds_read_b64_tr_b16 v[76:77], v231 offset:39936
	ds_read_b64_tr_b16 v[78:79], v231 offset:40448
	s_waitcnt lgkmcnt(14)
	v_mfma_f32_32x32x16_bf16 v[52:67], v[136:139], v[80:83], v[52:67]
	v_exp_f32_e32 v100, v100
	v_exp_f32_e32 v101, v101
	v_add_u32_e32 v80, s26, v251
	ds_read_b128 v[72:75], v80
	ds_read_b128 v[68:71], v80 offset:512
	s_waitcnt lgkmcnt(14)
	v_mfma_f32_32x32x16_bf16 v[36:51], v[136:139], v[84:87], v[36:51]
	v_exp_f32_e32 v102, v102
	v_exp_f32_e32 v103, v103
	ds_read_b128 v[184:187], v80 offset:2048
	ds_read_b128 v[180:183], v80 offset:2560
	s_waitcnt lgkmcnt(14)
	v_mfma_f32_32x32x16_bf16 v[20:35], v[136:139], v[88:91], v[20:35]
	v_exp_f32_e32 v104, v104
	v_exp_f32_e32 v105, v105
	ds_read_b128 v[176:179], v80 offset:4096
	ds_read_b128 v[172:175], v80 offset:4608
	s_waitcnt lgkmcnt(14)
	v_mfma_f32_32x32x16_bf16 v[4:19], v[136:139], v[92:95], v[4:19]
	v_exp_f32_e32 v106, v106
	v_exp_f32_e32 v107, v107
	ds_read_b128 v[168:171], v80 offset:6144
	ds_read_b128 v[164:167], v80 offset:6656
	s_waitcnt lgkmcnt(14)
	v_mfma_f32_32x32x16_bf16 v[52:67], v[132:135], v[96:99], v[52:67]
	v_exp_f32_e32 v108, v108
	v_exp_f32_e32 v109, v109
	s_add_i32 m0, s38, s31
	v_lshl_add_u64 v[198:199], s[2:3], 0, v[200:201]
	v_lshl_add_u64 v[80:81], v[198:199], 0, s[84:85]
	global_load_lds_dwordx4 v[80:81], off
	s_waitcnt lgkmcnt(12)
	v_mfma_f32_32x32x16_bf16 v[36:51], v[132:135], v[188:191], v[36:51]
	v_exp_f32_e32 v110, v110
	v_exp_f32_e32 v111, v111
	s_lshl_b32 s41, s26, 1
	s_add_i32 m0, s41, s34
	v_lshl_add_u64 v[196:197], s[2:3], 0, v[202:203]
	v_lshl_add_u64 v[80:81], v[196:197], 0, s[86:87]
	global_load_lds_dwordx4 v[80:81], off
	s_waitcnt lgkmcnt(10)
	v_mfma_f32_32x32x16_bf16 v[20:35], v[132:135], v[206:209], v[20:35]
	v_exp_f32_e32 v112, v112
	v_exp_f32_e32 v113, v113
	s_add_i32 m0, m0, 0x2000
	v_lshl_add_u64 v[80:81], v[196:197], 0, s[88:89]
	global_load_lds_dwordx4 v[80:81], off
	s_waitcnt lgkmcnt(8)
	v_mfma_f32_32x32x16_bf16 v[4:19], v[132:135], v[76:79], v[4:19]
	v_exp_f32_e32 v114, v114
	v_exp_f32_e32 v115, v115
	s_waitcnt vmcnt(3) lgkmcnt(0)
	s_barrier
	s_andn2_b64 vcc, exec, s[6:7]
	s_cbranch_vccnz .LBB0_497
	s_waitcnt lgkmcnt(0)
	v_add_u32_e32 v88, s29, v204
	ds_read_b128 v[76:79], v88 offset:96
	ds_read_b128 v[80:83], v88 offset:64
	ds_read_b128 v[84:87], v88 offset:32
	ds_read_b128 v[88:91], v88
	s_waitcnt lgkmcnt(3)
	v_pk_mul_f32 v[64:65], v[64:65], v[76:77]
	s_waitcnt lgkmcnt(2)
	v_pk_mul_f32 v[60:61], v[60:61], v[80:81]
	s_waitcnt lgkmcnt(1)
	v_pk_mul_f32 v[56:57], v[56:57], v[84:85]
	v_pk_mul_f32 v[66:67], v[66:67], v[78:79]
	v_pk_mul_f32 v[62:63], v[62:63], v[82:83]
	v_pk_mul_f32 v[58:59], v[58:59], v[86:87]
	s_waitcnt lgkmcnt(0)
	v_pk_mul_f32 v[54:55], v[54:55], v[90:91]
	v_pk_mul_f32 v[52:53], v[52:53], v[88:89]
	v_pk_mul_f32 v[48:49], v[48:49], v[76:77]
	v_pk_mul_f32 v[44:45], v[44:45], v[80:81]
	v_pk_mul_f32 v[40:41], v[40:41], v[84:85]
	v_pk_mul_f32 v[50:51], v[50:51], v[78:79]
	v_pk_mul_f32 v[46:47], v[46:47], v[82:83]
	v_pk_mul_f32 v[42:43], v[42:43], v[86:87]
	v_pk_mul_f32 v[38:39], v[38:39], v[90:91]
	v_pk_mul_f32 v[36:37], v[36:37], v[88:89]
	v_pk_mul_f32 v[32:33], v[32:33], v[76:77]
	v_pk_mul_f32 v[28:29], v[28:29], v[80:81]
	v_pk_mul_f32 v[24:25], v[24:25], v[84:85]
	v_pk_mul_f32 v[34:35], v[34:35], v[78:79]
	v_pk_mul_f32 v[30:31], v[30:31], v[82:83]
	v_pk_mul_f32 v[26:27], v[26:27], v[86:87]
	v_pk_mul_f32 v[22:23], v[22:23], v[90:91]
	v_pk_mul_f32 v[20:21], v[20:21], v[88:89]
	v_pk_mul_f32 v[16:17], v[16:17], v[76:77]
	v_pk_mul_f32 v[12:13], v[12:13], v[80:81]
	v_pk_mul_f32 v[8:9], v[8:9], v[84:85]
	v_pk_mul_f32 v[18:19], v[18:19], v[78:79]
	v_pk_mul_f32 v[14:15], v[14:15], v[82:83]
	v_pk_mul_f32 v[10:11], v[10:11], v[86:87]
	v_pk_mul_f32 v[6:7], v[6:7], v[90:91]
	v_pk_mul_f32 v[4:5], v[4:5], v[88:89]

.LBB0_498:
	s_add_i32 s12, s26, 0x2000
	s_cmpk_lg_i32 s26, 0x4000
	s_cselect_b32 s38, s12, 0
	s_waitcnt lgkmcnt(14)
	v_mfma_f32_32x32x16_bf16 v[52:67], v[144:147], v[188:191], v[52:67]
	v_exp_f32_e32 v84, v84
	v_exp_f32_e32 v85, v85
	ds_read_b64_tr_b16 v[112:113], v193 offset:26624
	ds_read_b64_tr_b16 v[114:115], v193 offset:27136
	s_waitcnt lgkmcnt(14)
	v_mfma_f32_32x32x16_bf16 v[36:51], v[144:147], v[116:119], v[36:51]
	v_exp_f32_e32 v86, v86
	v_exp_f32_e32 v87, v87
	ds_read_b64_tr_b16 v[116:117], v193 offset:30720
	ds_read_b64_tr_b16 v[118:119], v193 offset:31232
	s_waitcnt lgkmcnt(14)
	v_mfma_f32_32x32x16_bf16 v[20:35], v[144:147], v[120:123], v[20:35]
	v_exp_f32_e32 v88, v88
	v_exp_f32_e32 v89, v89
	ds_read_b64_tr_b16 v[120:121], v193 offset:34816
	ds_read_b64_tr_b16 v[122:123], v193 offset:35328
	s_waitcnt lgkmcnt(14)
	v_mfma_f32_32x32x16_bf16 v[4:19], v[144:147], v[124:127], v[4:19]
	v_exp_f32_e32 v90, v90
	v_exp_f32_e32 v91, v91
	ds_read_b64_tr_b16 v[124:125], v193 offset:38912
	ds_read_b64_tr_b16 v[126:127], v193 offset:39424
	s_waitcnt lgkmcnt(14)
	v_mfma_f32_32x32x16_bf16 v[52:67], v[140:143], v[128:131], v[52:67]
	v_exp_f32_e32 v92, v92
	v_exp_f32_e32 v93, v93
	ds_read_b64_tr_b16 v[128:129], v193 offset:27648
	ds_read_b64_tr_b16 v[130:131], v193 offset:28160
	s_waitcnt lgkmcnt(14)
	v_mfma_f32_32x32x16_bf16 v[36:51], v[140:143], v[100:103], v[36:51]
	v_exp_f32_e32 v94, v94
	v_exp_f32_e32 v95, v95
	ds_read_b64_tr_b16 v[100:101], v193 offset:31744
	ds_read_b64_tr_b16 v[102:103], v193 offset:32256
	s_waitcnt lgkmcnt(14)
	v_mfma_f32_32x32x16_bf16 v[20:35], v[140:143], v[104:107], v[20:35]
	v_exp_f32_e32 v96, v96
	v_exp_f32_e32 v97, v97
	ds_read_b64_tr_b16 v[104:105], v193 offset:35840
	ds_read_b64_tr_b16 v[106:107], v193 offset:36352
	s_waitcnt lgkmcnt(14)
	v_mfma_f32_32x32x16_bf16 v[4:19], v[140:143], v[108:111], v[4:19]
	v_exp_f32_e32 v98, v98
	v_exp_f32_e32 v99, v99
	ds_read_b64_tr_b16 v[108:109], v193 offset:39936
	ds_read_b64_tr_b16 v[110:111], v193 offset:40448
	s_waitcnt lgkmcnt(14)
	v_mfma_f32_32x32x16_bf16 v[52:67], v[136:139], v[112:115], v[52:67]
	v_exp_f32_e32 v68, v68
	v_exp_f32_e32 v69, v69
	v_add_u32_e32 v112, s38, v251
	ds_read_b128 v[192:195], v112
	ds_read_b128 v[188:191], v112 offset:512
	s_waitcnt lgkmcnt(14)
	v_mfma_f32_32x32x16_bf16 v[36:51], v[136:139], v[116:119], v[36:51]
	v_exp_f32_e32 v70, v70
	v_exp_f32_e32 v71, v71
	ds_read_b128 v[184:187], v112 offset:2048
	ds_read_b128 v[180:183], v112 offset:2560
	s_waitcnt lgkmcnt(14)
	v_mfma_f32_32x32x16_bf16 v[20:35], v[136:139], v[120:123], v[20:35]
	v_exp_f32_e32 v72, v72
	v_exp_f32_e32 v73, v73
	ds_read_b128 v[176:179], v112 offset:4096
	ds_read_b128 v[172:175], v112 offset:4608
	s_waitcnt lgkmcnt(14)
	v_mfma_f32_32x32x16_bf16 v[4:19], v[136:139], v[124:127], v[4:19]
	v_exp_f32_e32 v74, v74
	v_exp_f32_e32 v75, v75
	ds_read_b128 v[168:171], v112 offset:6144
	ds_read_b128 v[164:167], v112 offset:6656
	s_waitcnt lgkmcnt(14)
	v_mfma_f32_32x32x16_bf16 v[52:67], v[132:135], v[128:131], v[52:67]
	v_exp_f32_e32 v76, v76
	v_exp_f32_e32 v77, v77
	s_add_i32 m0, s26, s31
	v_lshl_add_u64 v[112:113], v[198:199], 0, s[90:91]
	global_load_lds_dwordx4 v[112:113], off
	s_waitcnt lgkmcnt(12)
	v_mfma_f32_32x32x16_bf16 v[36:51], v[132:135], v[100:103], v[36:51]
	v_exp_f32_e32 v78, v78
	v_exp_f32_e32 v79, v79
	s_lshl_b32 s12, s38, 1
	s_add_i32 m0, s12, s34
	v_lshl_add_u64 v[100:101], v[196:197], 0, s[92:93]
	global_load_lds_dwordx4 v[100:101], off
	s_waitcnt lgkmcnt(10)
	v_mfma_f32_32x32x16_bf16 v[20:35], v[132:135], v[104:107], v[20:35]
	v_exp_f32_e32 v80, v80
	v_exp_f32_e32 v81, v81
	s_add_i32 m0, m0, 0x2000
	v_lshl_add_u64 v[100:101], v[196:197], 0, s[94:95]
	global_load_lds_dwordx4 v[100:101], off
	s_waitcnt lgkmcnt(8)
	v_mfma_f32_32x32x16_bf16 v[4:19], v[132:135], v[108:111], v[4:19]
	v_exp_f32_e32 v82, v82
	v_exp_f32_e32 v83, v83
	s_waitcnt vmcnt(3) lgkmcnt(0)
	s_barrier
	s_andn2_b64 vcc, exec, s[6:7]
	s_cbranch_vccnz .LBB0_500
	s_waitcnt lgkmcnt(0)
	v_add_u32_e32 v112, s29, v204
	ds_read_b128 v[100:103], v112 offset:96
	ds_read_b128 v[104:107], v112 offset:64
	ds_read_b128 v[108:111], v112 offset:32
	ds_read_b128 v[112:115], v112
	s_waitcnt lgkmcnt(3)
	v_pk_mul_f32 v[64:65], v[64:65], v[100:101]
	s_waitcnt lgkmcnt(2)
	v_pk_mul_f32 v[60:61], v[60:61], v[104:105]
	s_waitcnt lgkmcnt(1)
	v_pk_mul_f32 v[56:57], v[56:57], v[108:109]
	v_pk_mul_f32 v[66:67], v[66:67], v[102:103]
	v_pk_mul_f32 v[62:63], v[62:63], v[106:107]
	v_pk_mul_f32 v[58:59], v[58:59], v[110:111]
	s_waitcnt lgkmcnt(0)
	v_pk_mul_f32 v[54:55], v[54:55], v[114:115]
	v_pk_mul_f32 v[52:53], v[52:53], v[112:113]
	v_pk_mul_f32 v[48:49], v[48:49], v[100:101]
	v_pk_mul_f32 v[44:45], v[44:45], v[104:105]
	v_pk_mul_f32 v[40:41], v[40:41], v[108:109]
	v_pk_mul_f32 v[50:51], v[50:51], v[102:103]
	v_pk_mul_f32 v[46:47], v[46:47], v[106:107]
	v_pk_mul_f32 v[42:43], v[42:43], v[110:111]
	v_pk_mul_f32 v[38:39], v[38:39], v[114:115]
	v_pk_mul_f32 v[36:37], v[36:37], v[112:113]
	v_pk_mul_f32 v[32:33], v[32:33], v[100:101]
	v_pk_mul_f32 v[28:29], v[28:29], v[104:105]
	v_pk_mul_f32 v[24:25], v[24:25], v[108:109]
	v_pk_mul_f32 v[34:35], v[34:35], v[102:103]
	v_pk_mul_f32 v[30:31], v[30:31], v[106:107]
	v_pk_mul_f32 v[26:27], v[26:27], v[110:111]
	v_pk_mul_f32 v[22:23], v[22:23], v[114:115]
	v_pk_mul_f32 v[20:21], v[20:21], v[112:113]
	v_pk_mul_f32 v[16:17], v[16:17], v[100:101]
	v_pk_mul_f32 v[12:13], v[12:13], v[104:105]
	v_pk_mul_f32 v[8:9], v[8:9], v[108:109]
	v_pk_mul_f32 v[18:19], v[18:19], v[102:103]
	v_pk_mul_f32 v[14:15], v[14:15], v[106:107]
	v_pk_mul_f32 v[10:11], v[10:11], v[110:111]
	v_pk_mul_f32 v[6:7], v[6:7], v[114:115]
	v_pk_mul_f32 v[4:5], v[4:5], v[112:113]
